# attention O epilogue: 16x store_dwordx2 widened to 8x store_dwordx4 via v_permlane32_swap (on top of saddr K-loop loads)
# speedup vs baseline: 1.0125x; 1.0058x over previous
; __device__ __forceinline__ unsigned pk2(float lo, float hi) { unsigned r; asm("v_cvt_pk_bf16_f32 %0, %1, %2" : "=v"(r) : "v"(lo), "v"(hi)); return r; }
; __device__ __forceinline__ void phase_attn_items(const Params& P, LAS unsigned char* lds) {
;     ...
;         const float inv = 1.f / sum;
;         bf16_t* op = OpB + (size_t)pat * MTOK * AW + qrow * AW + hh * 128 + 4 * h;
; #pragma unroll
;         for (int c = 0; c < 4; ++c)
; #pragma unroll
;             for (int g = 0; g < 4; ++g) { u32x2 w; w.x = pk2(O[c][4 * g] * inv, O[c][4 * g + 1] * inv); w.y = pk2(O[c][4 * g + 2] * inv, O[c][4 * g + 3] * inv);
;                 *(u32x2*)(op + 32 * c + 8 * g) = w; }
;         if (h == 0) LseB[(size_t)pat * MTOK * 8 + qrow * 8 + hh] = (mx + __builtin_amdgcn_logf(sum)) * LN2F;
.LBB0_195:
	v_add_f32_e32 v0, v81, v165
	v_div_scale_f32 v4, s[2:3], v0, v0, 1.0
	v_rcp_f32_e32 v5, v4
	s_ashr_i32 s27, s26, 31
	s_lshl_b64 s[2:3], s[26:27], 25
	v_readlane_b32 s4, v247, 9
	v_fma_f32 v6, -v4, v5, 1.0
	v_fmac_f32_e32 v5, v6, v5
	v_div_scale_f32 v6, vcc, 1.0, v0, 1.0
	v_mul_f32_e32 v7, v6, v5
	v_fma_f32 v8, -v4, v7, v6
	v_fmac_f32_e32 v7, v8, v5
	v_fma_f32 v4, -v4, v7, v6
	v_div_fmas_f32 v4, v4, v5, v7
	s_add_u32 s2, s4, s2
	v_readlane_b32 s4, v247, 10
	v_lshlrev_b64 v[2:3], 10, v[162:163]
	v_div_fixup_f32 v6, v4, v0, 1.0
	s_addc_u32 s3, s4, s3
	v_lshl_add_u64 v[2:3], v[2:3], 1, s[2:3]
	v_lshl_add_u64 v[2:3], s[72:73], 1, v[2:3]
	v_ashrrev_i32_e32 v165, 31, v164
	v_lshl_add_u64 v[2:3], v[164:165], 1, v[2:3]
	v_lshl_add_u64 v[2:3], v[164:165], 1, v[2:3]
	v_pk_mul_f32 v[64:65], v[64:65], v[6:7] op_sel_hi:[1,0]
	v_pk_mul_f32 v[66:67], v[66:67], v[6:7] op_sel_hi:[1,0]
	v_pk_mul_f32 v[68:69], v[68:69], v[6:7] op_sel_hi:[1,0]
	v_pk_mul_f32 v[70:71], v[70:71], v[6:7] op_sel_hi:[1,0]
	v_cvt_pk_bf16_f32 v192, v64, v65
	v_cvt_pk_bf16_f32 v193, v66, v67
	v_cvt_pk_bf16_f32 v194, v68, v69
	v_cvt_pk_bf16_f32 v195, v70, v71
	s_nop 1
	v_permlane32_swap_b32 v192, v194
	v_permlane32_swap_b32 v193, v195
	flat_store_dwordx4 v[2:3], v[192:195]
	v_pk_mul_f32 v[72:73], v[72:73], v[6:7] op_sel_hi:[1,0]
	v_pk_mul_f32 v[74:75], v[74:75], v[6:7] op_sel_hi:[1,0]
	v_pk_mul_f32 v[76:77], v[76:77], v[6:7] op_sel_hi:[1,0]
	v_pk_mul_f32 v[78:79], v[78:79], v[6:7] op_sel_hi:[1,0]
	v_cvt_pk_bf16_f32 v196, v72, v73
	v_cvt_pk_bf16_f32 v197, v74, v75
	v_cvt_pk_bf16_f32 v198, v76, v77
	v_cvt_pk_bf16_f32 v199, v78, v79
	s_nop 1
	v_permlane32_swap_b32 v196, v198
	v_permlane32_swap_b32 v197, v199
	flat_store_dwordx4 v[2:3], v[196:199] offset:32
	v_pk_mul_f32 v[48:49], v[48:49], v[6:7] op_sel_hi:[1,0]
	v_pk_mul_f32 v[50:51], v[50:51], v[6:7] op_sel_hi:[1,0]
	v_pk_mul_f32 v[52:53], v[52:53], v[6:7] op_sel_hi:[1,0]
	v_pk_mul_f32 v[54:55], v[54:55], v[6:7] op_sel_hi:[1,0]
	v_cvt_pk_bf16_f32 v200, v48, v49
	v_cvt_pk_bf16_f32 v201, v50, v51
	v_cvt_pk_bf16_f32 v202, v52, v53
	v_cvt_pk_bf16_f32 v203, v54, v55
	s_nop 1
	v_permlane32_swap_b32 v200, v202
	v_permlane32_swap_b32 v201, v203
	flat_store_dwordx4 v[2:3], v[200:203] offset:64
	v_pk_mul_f32 v[56:57], v[56:57], v[6:7] op_sel_hi:[1,0]
	v_pk_mul_f32 v[58:59], v[58:59], v[6:7] op_sel_hi:[1,0]
	v_pk_mul_f32 v[60:61], v[60:61], v[6:7] op_sel_hi:[1,0]
	v_pk_mul_f32 v[62:63], v[62:63], v[6:7] op_sel_hi:[1,0]
	v_cvt_pk_bf16_f32 v204, v56, v57
	v_cvt_pk_bf16_f32 v205, v58, v59
	v_cvt_pk_bf16_f32 v206, v60, v61
	v_cvt_pk_bf16_f32 v207, v62, v63
	s_nop 1
	v_permlane32_swap_b32 v204, v206
	v_permlane32_swap_b32 v205, v207
	flat_store_dwordx4 v[2:3], v[204:207] offset:96
	v_pk_mul_f32 v[32:33], v[32:33], v[6:7] op_sel_hi:[1,0]
	v_pk_mul_f32 v[34:35], v[34:35], v[6:7] op_sel_hi:[1,0]
	v_pk_mul_f32 v[36:37], v[36:37], v[6:7] op_sel_hi:[1,0]
	v_pk_mul_f32 v[38:39], v[38:39], v[6:7] op_sel_hi:[1,0]
	v_cvt_pk_bf16_f32 v192, v32, v33
	v_cvt_pk_bf16_f32 v193, v34, v35
	v_cvt_pk_bf16_f32 v194, v36, v37
	v_cvt_pk_bf16_f32 v195, v38, v39
	s_nop 1
	v_permlane32_swap_b32 v192, v194
	v_permlane32_swap_b32 v193, v195
	flat_store_dwordx4 v[2:3], v[192:195] offset:128
	v_pk_mul_f32 v[40:41], v[40:41], v[6:7] op_sel_hi:[1,0]
	v_pk_mul_f32 v[42:43], v[42:43], v[6:7] op_sel_hi:[1,0]
	v_pk_mul_f32 v[44:45], v[44:45], v[6:7] op_sel_hi:[1,0]
	v_pk_mul_f32 v[46:47], v[46:47], v[6:7] op_sel_hi:[1,0]
	v_cvt_pk_bf16_f32 v196, v40, v41
	v_cvt_pk_bf16_f32 v197, v42, v43
	v_cvt_pk_bf16_f32 v198, v44, v45
	v_cvt_pk_bf16_f32 v199, v46, v47
	s_nop 1
	v_permlane32_swap_b32 v196, v198
	v_permlane32_swap_b32 v197, v199
	flat_store_dwordx4 v[2:3], v[196:199] offset:160
	v_pk_mul_f32 v[16:17], v[16:17], v[6:7] op_sel_hi:[1,0]
	v_pk_mul_f32 v[18:19], v[18:19], v[6:7] op_sel_hi:[1,0]
	v_pk_mul_f32 v[20:21], v[20:21], v[6:7] op_sel_hi:[1,0]
	v_pk_mul_f32 v[22:23], v[22:23], v[6:7] op_sel_hi:[1,0]
	v_cvt_pk_bf16_f32 v200, v16, v17
	v_cvt_pk_bf16_f32 v201, v18, v19
	v_cvt_pk_bf16_f32 v202, v20, v21
	v_cvt_pk_bf16_f32 v203, v22, v23
	s_nop 1
	v_permlane32_swap_b32 v200, v202
	v_permlane32_swap_b32 v201, v203
	flat_store_dwordx4 v[2:3], v[200:203] offset:192
	v_pk_mul_f32 v[24:25], v[24:25], v[6:7] op_sel_hi:[1,0]
	v_pk_mul_f32 v[26:27], v[26:27], v[6:7] op_sel_hi:[1,0]
	v_pk_mul_f32 v[28:29], v[28:29], v[6:7] op_sel_hi:[1,0]
	v_pk_mul_f32 v[30:31], v[30:31], v[6:7] op_sel_hi:[1,0]
	v_cvt_pk_bf16_f32 v204, v24, v25
	v_cvt_pk_bf16_f32 v205, v26, v27
	v_cvt_pk_bf16_f32 v206, v28, v29
	v_cvt_pk_bf16_f32 v207, v30, v31
	s_nop 1
	v_permlane32_swap_b32 v204, v206
	v_permlane32_swap_b32 v205, v207
	flat_store_dwordx4 v[2:3], v[204:207] offset:224
	v_cmp_gt_u32_e32 vcc, 32, v174
	s_and_saveexec_b64 s[24:25], vcc
	s_cbranch_execz .LBB0_113
	v_log_f32_e32 v0, v0
	s_lshl_b64 s[2:3], s[26:27], 19
	v_readlane_b32 s4, v247, 11
	s_add_u32 s2, s4, s2
	v_readlane_b32 s4, v247, 12
	s_addc_u32 s3, s4, s3
	v_lshlrev_b64 v[2:3], 5, v[162:163]
	v_add_f32_e32 v0, v80, v0
	v_lshl_add_u64 v[2:3], s[2:3], 0, v[2:3]
	v_mul_f32_e32 v0, 0x3f317218, v0
	v_lshl_add_u64 v[2:3], s[16:17], 2, v[2:3]
	flat_store_dword v[2:3], v0
	s_branch .LBB0_113
